# v110 + RmsStats L1-invalidate dropped (sc1 loads only) + v_mov_b64 acc zero-init + attention sink logit via scalar load issued at commit
# baseline (speedup 1.0000x reference)
;     __host__ __device__ bool next(int i, Unit& u) const { if (!S.next(i, u)) return false; u.pn = u.pn < cut ? u.pn + add_lo : u.pn + add_hi; u.pm += pm_add; return true; }
;     __host__ __device__ bool next(int i, Unit& o) const { if (i != 0 || !have) return false; o = u; return true; }
; template <class Epi, class Sched, bool ALIGN_EPI = false, bool SP2 = false, bool FP8 = false>
; __device__ __forceinline__ void gemm_phase(PG8_LAS unsigned char* lds, const Gemm g, const Sched& S, const Epi& E) {
;     ...
;         const bool has_next = S.next(ui + 1, nxt);
;         const char* nA = has_next ? (const char*)g.A + (size_t)nxt.pz * g.zA * 2 + (size_t)nxt.pm * tstepA : cA; const char* nB = has_next ? (const char*)g.Bt + (size_t)nxt.pz * g.zB * 2 + (size_t)nxt.pn * tstepB : cB;
;     ...
; #pragma unroll
;         for (int a = 0; a < 2; ++a)
; #pragma unroll
;             for (int b = 0; b < 2; ++b)
; #pragma unroll
;                 for (int m = 0; m < 4; ++m)
; #pragma unroll
;                     for (int n = 0; n < 2; ++n) acc[a][b][m][n] = (f32x4){0.f, 0.f, 0.f, 0.f};
;         cur = nxt; cA = nA; cB = nB; ++ui;
.LBB0_217:
	s_mov_b32 s1, s93
	s_add_i32 s93, s93, 5
	s_and_b64 s[46:47], s[44:45], exec
	s_cselect_b32 s48, s93, s1
	s_cselect_b32 s1, s11, 0
	s_add_i32 s42, s1, s42
	s_ashr_i32 s43, s42, 31
	s_lshl_b64 s[46:47], s[42:43], 18
	s_add_u32 s46, s37, s46
	s_addc_u32 s47, s39, s47
	s_and_b64 s[68:69], s[44:45], exec
	s_cselect_b32 s1, s47, s55
	s_cselect_b32 s43, s46, s54
	s_ashr_i32 s49, s48, 31
	s_lshl_b64 s[48:49], s[48:49], 18
	s_add_u32 s48, s63, s48
	s_addc_u32 s49, s81, s49
	s_and_b64 s[68:69], s[44:45], exec
	s_cselect_b32 s53, s49, s57
	s_cselect_b32 s94, s48, s56
	s_add_u32 s54, s54, 0x20080
	s_addc_u32 s55, s55, 0
	s_add_u32 s95, s56, 0x100
	v_mov_b32_e32 v26, 0
	s_addc_u32 s96, s57, 0
	s_mov_b32 s33, -2
	v_mov_b32_e32 v27, v26
	v_mov_b64_e32 v[28:29], v[26:27]
	v_mov_b64_e32 v[30:31], v[26:27]
	v_mov_b64_e32 v[32:33], v[26:27]
	v_mov_b64_e32 v[34:35], v[26:27]
	v_mov_b64_e32 v[36:37], v[26:27]
	v_mov_b64_e32 v[38:39], v[26:27]
	v_mov_b64_e32 v[40:41], v[26:27]
	v_mov_b64_e32 v[42:43], v[26:27]
	v_mov_b64_e32 v[44:45], v[26:27]
	v_mov_b64_e32 v[46:47], v[26:27]
	v_mov_b64_e32 v[48:49], v[26:27]
	v_mov_b64_e32 v[50:51], v[26:27]
	v_mov_b64_e32 v[52:53], v[26:27]
	v_mov_b64_e32 v[54:55], v[26:27]
	v_mov_b64_e32 v[56:57], v[26:27]
	v_mov_b64_e32 v[58:59], v[26:27]
	v_mov_b64_e32 v[60:61], v[26:27]
	v_mov_b64_e32 v[62:63], v[26:27]
	v_mov_b64_e32 v[64:65], v[26:27]
	v_mov_b64_e32 v[66:67], v[26:27]
	v_mov_b64_e32 v[68:69], v[26:27]
	v_mov_b64_e32 v[70:71], v[26:27]
	v_mov_b64_e32 v[72:73], v[26:27]
	v_mov_b64_e32 v[74:75], v[26:27]
	v_mov_b64_e32 v[76:77], v[26:27]
	v_mov_b64_e32 v[78:79], v[26:27]
	v_mov_b64_e32 v[80:81], v[26:27]
	v_mov_b64_e32 v[82:83], v[26:27]
	v_mov_b64_e32 v[84:85], v[26:27]
	v_mov_b64_e32 v[86:87], v[26:27]
	v_mov_b64_e32 v[88:89], v[26:27]
	v_mov_b64_e32 v[90:91], v[26:27]
	v_mov_b64_e32 v[92:93], v[26:27]
	v_mov_b64_e32 v[94:95], v[26:27]
	v_mov_b64_e32 v[96:97], v[26:27]
	v_mov_b64_e32 v[98:99], v[26:27]
	v_mov_b64_e32 v[100:101], v[26:27]
	v_mov_b64_e32 v[102:103], v[26:27]
	v_mov_b64_e32 v[104:105], v[26:27]
	v_mov_b64_e32 v[106:107], v[26:27]
	v_mov_b64_e32 v[108:109], v[26:27]
	v_mov_b64_e32 v[110:111], v[26:27]
	v_mov_b64_e32 v[112:113], v[26:27]
	v_mov_b64_e32 v[114:115], v[26:27]
	v_mov_b64_e32 v[116:117], v[26:27]
	v_mov_b64_e32 v[118:119], v[26:27]
	v_mov_b64_e32 v[120:121], v[26:27]
	v_mov_b64_e32 v[122:123], v[26:27]
	v_mov_b64_e32 v[124:125], v[26:27]
	v_mov_b64_e32 v[126:127], v[26:27]
	v_mov_b64_e32 v[128:129], v[26:27]
	v_mov_b64_e32 v[130:131], v[26:27]
	v_mov_b64_e32 v[132:133], v[26:27]
	v_mov_b64_e32 v[134:135], v[26:27]
	v_mov_b64_e32 v[136:137], v[26:27]
	v_mov_b64_e32 v[138:139], v[26:27]
	v_mov_b64_e32 v[140:141], v[26:27]
	v_mov_b64_e32 v[142:143], v[26:27]
	v_mov_b64_e32 v[144:145], v[26:27]
	v_mov_b64_e32 v[146:147], v[26:27]
	v_mov_b64_e32 v[148:149], v[26:27]
	v_mov_b64_e32 v[150:151], v[26:27]
	v_mov_b64_e32 v[152:153], v[26:27]

;     __host__ __device__ bool next(int i, Unit& o) const { if (i != 0 || !have) return false; o = u; return true; }
;     __host__ __device__ bool next(int i, Unit& u) const { if (!S.next(i, u)) return false; u.pn = u.pn < cut ? u.pn + add_lo : u.pn + add_hi; u.pm += pm_add; return true; }
; template <class Epi, class Sched, bool ALIGN_EPI = false, bool SP2 = false, bool FP8 = false>
; __device__ __forceinline__ void gemm_phase(PG8_LAS unsigned char* lds, const Gemm g, const Sched& S, const Epi& E) {
;     ...
;         const bool has_next = S.next(ui + 1, nxt);
;         const char* nA = has_next ? (const char*)g.A + (size_t)nxt.pz * g.zA * 2 + (size_t)nxt.pm * tstepA : cA; const char* nB = has_next ? (const char*)g.Bt + (size_t)nxt.pz * g.zB * 2 + (size_t)nxt.pn * tstepB : cB;
;     ...
; #pragma unroll
;         for (int a = 0; a < 2; ++a)
; #pragma unroll
;             for (int b = 0; b < 2; ++b)
; #pragma unroll
;                 for (int m = 0; m < 4; ++m)
; #pragma unroll
;                     for (int n = 0; n < 2; ++n) acc[a][b][m][n] = (f32x4){0.f, 0.f, 0.f, 0.f};
;         cur = nxt; cA = nA; cB = nB; ++ui;
.LBB0_329:
	s_cmp_lt_i32 s48, 5
	s_cselect_b32 s1, 0, 2
	s_and_b64 s[54:55], s[52:53], exec
	s_cselect_b32 s1, s1, 0
	s_add_i32 s48, s1, s48
	s_and_b64 s[54:55], s[52:53], exec
	s_cselect_b32 s1, s82, 0
	s_add_i32 s46, s1, s46
	s_ashr_i32 s47, s46, 31
	s_lshl_b64 s[54:55], s[46:47], 18
	s_add_u32 s54, s11, s54
	s_addc_u32 s55, s83, s55
	s_and_b64 s[56:57], s[52:53], exec
	s_cselect_b32 s1, s55, s69
	s_cselect_b32 s47, s54, s68
	s_ashr_i32 s49, s48, 31
	s_lshl_b64 s[56:57], s[48:49], 18
	s_add_u32 s56, s63, s56
	s_addc_u32 s57, s81, s57
	s_and_b64 s[72:73], s[52:53], exec
	s_cselect_b32 s49, s57, s71
	s_cselect_b32 vcc_lo, s56, s70
	s_add_u32 s68, s68, 0x20080
	s_addc_u32 s69, s69, 0
	s_add_u32 vcc_hi, s70, 0x100
	v_mov_b32_e32 v26, 0
	s_addc_u32 s33, s71, 0
	s_mov_b32 s80, -2
	v_mov_b32_e32 v27, v26
	v_mov_b64_e32 v[28:29], v[26:27]
	v_mov_b64_e32 v[30:31], v[26:27]
	v_mov_b64_e32 v[32:33], v[26:27]
	v_mov_b64_e32 v[34:35], v[26:27]
	v_mov_b64_e32 v[36:37], v[26:27]
	v_mov_b64_e32 v[38:39], v[26:27]
	v_mov_b64_e32 v[40:41], v[26:27]
	v_mov_b64_e32 v[42:43], v[26:27]
	v_mov_b64_e32 v[44:45], v[26:27]
	v_mov_b64_e32 v[46:47], v[26:27]
	v_mov_b64_e32 v[48:49], v[26:27]
	v_mov_b64_e32 v[50:51], v[26:27]
	v_mov_b64_e32 v[52:53], v[26:27]
	v_mov_b64_e32 v[54:55], v[26:27]
	v_mov_b64_e32 v[56:57], v[26:27]
	v_mov_b64_e32 v[58:59], v[26:27]
	v_mov_b64_e32 v[60:61], v[26:27]
	v_mov_b64_e32 v[62:63], v[26:27]
	v_mov_b64_e32 v[64:65], v[26:27]
	v_mov_b64_e32 v[66:67], v[26:27]
	v_mov_b64_e32 v[68:69], v[26:27]
	v_mov_b64_e32 v[70:71], v[26:27]
	v_mov_b64_e32 v[72:73], v[26:27]
	v_mov_b64_e32 v[74:75], v[26:27]
	v_mov_b64_e32 v[76:77], v[26:27]
	v_mov_b64_e32 v[78:79], v[26:27]
	v_mov_b64_e32 v[80:81], v[26:27]
	v_mov_b64_e32 v[82:83], v[26:27]
	v_mov_b64_e32 v[84:85], v[26:27]
	v_mov_b64_e32 v[86:87], v[26:27]
	v_mov_b64_e32 v[88:89], v[26:27]
	v_mov_b64_e32 v[90:91], v[26:27]
	v_mov_b64_e32 v[92:93], v[26:27]
	v_mov_b64_e32 v[94:95], v[26:27]
	v_mov_b64_e32 v[96:97], v[26:27]
	v_mov_b64_e32 v[98:99], v[26:27]
	v_mov_b64_e32 v[100:101], v[26:27]
	v_mov_b64_e32 v[102:103], v[26:27]
	v_mov_b64_e32 v[104:105], v[26:27]
	v_mov_b64_e32 v[106:107], v[26:27]
	v_mov_b64_e32 v[108:109], v[26:27]
	v_mov_b64_e32 v[110:111], v[26:27]
	v_mov_b64_e32 v[112:113], v[26:27]
	v_mov_b64_e32 v[114:115], v[26:27]
	v_mov_b64_e32 v[116:117], v[26:27]
	v_mov_b64_e32 v[118:119], v[26:27]
	v_mov_b64_e32 v[120:121], v[26:27]
	v_mov_b64_e32 v[122:123], v[26:27]
	v_mov_b64_e32 v[124:125], v[26:27]
	v_mov_b64_e32 v[126:127], v[26:27]
	v_mov_b64_e32 v[128:129], v[26:27]
	v_mov_b64_e32 v[130:131], v[26:27]
	v_mov_b64_e32 v[132:133], v[26:27]
	v_mov_b64_e32 v[134:135], v[26:27]
	v_mov_b64_e32 v[136:137], v[26:27]
	v_mov_b64_e32 v[138:139], v[26:27]
	v_mov_b64_e32 v[140:141], v[26:27]
	v_mov_b64_e32 v[142:143], v[26:27]
	v_mov_b64_e32 v[144:145], v[26:27]
	v_mov_b64_e32 v[146:147], v[26:27]
	v_mov_b64_e32 v[148:149], v[26:27]
	v_mov_b64_e32 v[150:151], v[26:27]
	v_mov_b64_e32 v[152:153], v[26:27]

; #define PROBE_BEGIN(id) unsigned long long pb_t0_##id = 0; if (PROBE_SEC == (id)) pb_t0_##id = __builtin_amdgcn_s_memrealtime();
; #define PROBE_END(id) if (PROBE_SEC == (id)) { const unsigned long long pb_t1_ = __builtin_amdgcn_s_memrealtime(), pb_dt_ = pb_t1_ - pb_t0_##id; while (__builtin_amdgcn_s_memrealtime() - pb_t1_ < pb_dt_) __builtin_amdgcn_s_sleep(4); }
; #define LAS __attribute__((address_space(3)))
; __device__ __forceinline__ void attn_commit(Frame& F, int id, const KvRegs& R) {
;     LAS unsigned char* lds = F.lds; const int tid = F.tid, kvh = id & 1;
;     PROBE_BEGIN(3)
; #pragma unroll
;     for (int i = 0; i < 6; ++i) { const int p = tid + 512 * i, row = p >> 3, pc = p & 7; *(LAS v4u*)(lds + OFF_K + row * KROW + pc * 16) = R.k[i]; }
; #pragma unroll
;     for (int i = 0; i < 6; ++i) { const int p = tid + 512 * i, d = p / 48, pc = p - d * 48;
;         *(LAS v2u*)(lds + OFF_V + d * VROW + pc * 16) = (v2u){R.v[i].x, R.v[i].y}; *(LAS v2u*)(lds + OFF_V + d * VROW + pc * 16 + 8) = (v2u){R.v[i].z, R.v[i].w}; }
;     LAS f32x4* BT4 = (LAS f32x4*)(lds + OFF_B);
;     {   const f32x4* src = (const f32x4*)(F.ws + WS_BT4) + kvh * 4 * NBT;
; #pragma unroll
;         for (int i = 0; i < 3; ++i) BT4[tid + 512 * i] = src[tid + 512 * i]; }
;     __syncthreads();
;     PROBE_END(3)
; }
; __device__ __forceinline__ void attn_compute(Frame& F, int id) {
;     ...
;     const float sk = sink[h] * LOG2E;
.LBB0_545:
	s_lshl_b32 s2, s33, 2
	s_and_b32 s45, s2, 4
	s_add_i32 s54, s27, s45
	s_lshl_b32 s54, s54, 2
	s_load_dword s55, s[20:21], s54
	s_mul_i32 s2, s45, 0x1800
	s_add_u32 s2, s25, s2
	s_addc_u32 s3, s26, 0
	v_mov_b32_e32 v201, v2
	v_lshl_add_u64 v[8:9], s[2:3], 0, v[200:201]
	v_add_co_u32_e32 v8, vcc, 0x2000, v8
	global_load_dwordx4 v[4:7], v200, s[2:3]
	s_nop 0
	v_addc_co_u32_e32 v9, vcc, 0, v9, vcc
	global_load_dwordx4 v[8:11], v[8:9], off
	s_nop 0
	global_load_dwordx4 v[12:15], v242, s[2:3]
	s_waitcnt vmcnt(4)
	ds_write_b128 v230, v[114:117]
	ds_write_b128 v231, v[118:121]
	s_waitcnt vmcnt(3)
	ds_write_b128 v232, v[126:129]
	ds_write_b128 v233, v[122:125]
	ds_write_b128 v234, v[130:133]
	ds_write_b128 v235, v[134:137]
	ds_write2_b64 v236, v[138:139], v[140:141] offset1:1
	ds_write2_b64 v237, v[142:143], v[144:145] offset1:1
	ds_write2_b64 v238, v[146:147], v[148:149] offset1:1
	ds_write2_b64 v239, v[150:151], v[152:153] offset1:1
	ds_write2_b64 v240, v[154:155], v[156:157] offset1:1
	ds_write2_b64 v241, v[158:159], v[160:161] offset1:1
	s_waitcnt vmcnt(2)
	ds_write_b128 v218, v[4:7]
	s_waitcnt vmcnt(1)
	ds_write_b128 v219, v[8:11]
	s_waitcnt vmcnt(0)
	ds_write_b128 v220, v[12:15]
	s_waitcnt lgkmcnt(0)
	s_barrier
	s_and_saveexec_b64 s[2:3], s[0:1]
	s_cbranch_execz .LBB0_549
	s_mov_b64 s[22:23], exec
	v_mbcnt_lo_u32_b32 v3, s22, 0
	v_mbcnt_hi_u32_b32 v3, s23, v3
	v_cmp_eq_u32_e32 vcc, 0, v3
	s_and_saveexec_b64 s[4:5], vcc
	s_cbranch_execz .LBB0_548
	s_bcnt1_i32_b64 s14, s[22:23]
	v_mov_b32_e32 v4, s14
	global_atomic_add v4, v2, v4, s[16:17] sc0

; #define PROBE_BEGIN(id) unsigned long long pb_t0_##id = 0; if (PROBE_SEC == (id)) pb_t0_##id = __builtin_amdgcn_s_memrealtime();
; #define LAS __attribute__((address_space(3)))
; __device__ __forceinline__ void attn_compute(Frame& F, int id) {
;     ...
;     const int lane = F.lane, wid = F.wave;
;     const int key0 = 128 * (n - 1);
;     PROBE_BEGIN(4)
;     const int g = wid >> 1, qh = wid & 1, h = kvh * 4 + g, r = lane & 31, hh = lane >> 5;
;     const float sk = sink[h] * LOG2E;
;     const size_t tok0 = (size_t)b * SEQ + 128 * n + 64 * qh + r;
;     bf16x8 qf[2][4];
; #pragma unroll
;     for (int qb = 0; qb < 2; ++qb)
; #pragma unroll
;         for (int st = 0; st < 4; ++st) qf[qb][st] = *(const bf16x8*)(Q + (tok0 + 32 * qb) * 512 + h * 64 + 16 * st + 8 * hh);
;     const LAS f32x4* BT4 = (const LAS f32x4*)(lds + OFF_B);
;     const int ktA = 2 * qh;
;     const LAS f32x4* BTg = BT4 + g * NBT + 63 - r + 4 * hh;
;     const LAS unsigned char* kbase = lds + OFF_K + (32 * ktA + r) * KROW + 16 * hh;
;     const LAS unsigned char* vbase = lds + OFF_V + r * VROW + (32 * ktA + 4 * hh) * 2;
;     float m0 = sk, m1 = sk, l0 = 0.f, l1 = 0.f;
;     f32x16 O0[2], O1[2];
; #pragma unroll
;     for (int q = 0; q < 16; ++q) { O0[0][q] = 0.f; O0[1][q] = 0.f; O1[0][q] = 0.f; O1[1][q] = 0.f; }
.LBB0_574:
	s_add_i32 s4, s33, s11
	s_lshl_b32 s5, s33, 6
	s_add_i32 s22, s27, s45
	s_ashr_i32 s4, s4, 5
	s_and_b32 s23, s5, 0x780
	s_lshl_b32 s5, s22, 2
	v_mov_b32_e32 v3, s5
	s_ashr_i32 s5, s4, 31
	s_lshl_b64 s[4:5], s[4:5], 11
	s_or_b32 s4, s4, s23
	v_mov_b32_e32 v205, s5
	v_or_b32_e32 v204, s4, v196
	s_lshl_b32 s14, s22, 7
	v_lshl_add_u64 v[4:5], v[198:199], 0, s[14:15]
	v_lshlrev_b64 v[206:207], 10, v[204:205]
	v_lshl_add_u64 v[4:5], v[4:5], 0, v[206:207]
	global_load_dwordx4 v[162:165], v[4:5], off
	global_load_dwordx4 v[166:169], v[4:5], off offset:32
	global_load_dwordx4 v[170:173], v[4:5], off offset:64
	global_load_dwordx4 v[174:177], v[4:5], off offset:96
	v_add_co_u32_e32 v4, vcc, s43, v4
	v_mov_b32_e32 v16, v2
	s_nop 0
	v_addc_co_u32_e32 v5, vcc, 0, v5, vcc
	global_load_dwordx4 v[178:181], v[4:5], off
	global_load_dwordx4 v[182:185], v[4:5], off offset:32
	global_load_dwordx4 v[186:189], v[4:5], off offset:64
	global_load_dwordx4 v[190:193], v[4:5], off offset:96
	v_mov_b32_e32 v17, v2
	v_mov_b32_e32 v3, v2
	v_mov_b32_e32 v4, v2
	v_mov_b32_e32 v5, v2
	v_mov_b32_e32 v6, v2
	v_mov_b32_e32 v7, v2
	v_mov_b32_e32 v8, v2
	v_mov_b32_e32 v9, v2
	v_mov_b32_e32 v10, v2
	v_mov_b32_e32 v11, v2
	v_mov_b32_e32 v12, v2
	v_mov_b32_e32 v13, v2
	v_mov_b32_e32 v14, v2
	v_mov_b32_e32 v15, v2
	v_mov_b64_e32 v[64:65], v[16:17]
	v_mov_b64_e32 v[80:81], v[16:17]
	v_mov_b64_e32 v[48:49], v[16:17]
	v_mov_b32_e32 v201, 0
	s_movk_i32 s14, 0xfee0
	v_mov_b32_e32 v203, v229
	v_mov_b32_e32 v247, v228
	v_mov_b32_e32 v248, v227
	s_lshl_b32 s22, s22, 6
	s_or_b32 s23, s36, s23
	v_mov_b64_e32 v[62:63], v[14:15]
	v_mov_b64_e32 v[60:61], v[12:13]
	v_mov_b64_e32 v[58:59], v[10:11]
	v_mov_b64_e32 v[56:57], v[8:9]
	v_mov_b64_e32 v[54:55], v[6:7]
	v_mov_b64_e32 v[52:53], v[4:5]
	v_mov_b64_e32 v[50:51], v[2:3]
	v_mov_b32_e32 v246, 0
	v_mov_b64_e32 v[78:79], v[14:15]
	v_mov_b64_e32 v[76:77], v[12:13]
	v_mov_b64_e32 v[74:75], v[10:11]
	v_mov_b64_e32 v[72:73], v[8:9]
	v_mov_b64_e32 v[70:71], v[6:7]
	v_mov_b64_e32 v[68:69], v[4:5]
	v_mov_b64_e32 v[66:67], v[2:3]
	v_mov_b64_e32 v[46:47], v[14:15]
	v_mov_b64_e32 v[44:45], v[12:13]
	v_mov_b64_e32 v[42:43], v[10:11]
	v_mov_b64_e32 v[40:41], v[8:9]
	v_mov_b64_e32 v[38:39], v[6:7]
	v_mov_b64_e32 v[36:37], v[4:5]
	v_mov_b64_e32 v[34:35], v[2:3]
	v_mov_b32_e32 v244, 0x3fb8aa3b
	s_waitcnt lgkmcnt(0)
	v_mul_f32_e32 v244, s55, v244
	v_mov_b64_e32 v[32:33], v[16:17]
	v_mov_b64_e32 v[30:31], v[14:15]
	v_mov_b64_e32 v[28:29], v[12:13]
	v_mov_b64_e32 v[26:27], v[10:11]
	v_mov_b64_e32 v[24:25], v[8:9]
	v_mov_b64_e32 v[22:23], v[6:7]
	v_mov_b64_e32 v[20:21], v[4:5]
	v_mov_b64_e32 v[18:19], v[2:3]
	v_mov_b32_e32 v245, v244
	v_mov_b32_e32 v249, v244
	s_branch .LBB0_576

;     __device__ __forceinline__ bool run(const f32x4 (&v)[2][2][4][2], const Unit& u, int wr, int wc, int fr, int fq, PG8_LAS unsigned char* lds, int wid, int lane) const {
;     ...
;         if (wid == 0) {
;             bool dead = false; const unsigned long long t0 = __builtin_amdgcn_s_memrealtime(); const unsigned want = 32u;
;             for (;;) {
;                 if ((unsigned)__builtin_amdgcn_readfirstlane(__hip_atomic_load(cnt + 64 * u.pm, __ATOMIC_RELAXED, __HIP_MEMORY_SCOPE_AGENT)) >= want) break;
;                 if (__builtin_amdgcn_s_memrealtime() - t0 > 2000000ull) { if (lane == 0) __hip_atomic_store(tmo, 1u, __ATOMIC_RELAXED, __HIP_MEMORY_SCOPE_AGENT); dead = true; break; }
;                 __builtin_amdgcn_s_sleep(2);
;             }
;             __builtin_amdgcn_fence(__ATOMIC_ACQUIRE, "agent");
;             if (lane == 0) flag[0] = dead ? 1u : 0u;
.LBB0_834:
	s_andn2_b64 vcc, exec, s[20:21]
	s_cbranch_vccz .LBB0_840
	s_and_saveexec_b64 s[16:17], s[4:5]
	s_xor_b64 s[4:5], exec, s[16:17]
	s_cbranch_execz .LBB0_837
	s_waitcnt lgkmcnt(0)
.LBB0_837:
	s_or_saveexec_b64 s[16:17], s[4:5]
	s_mov_b64 s[4:5], 0
	s_xor_b64 exec, exec, s[16:17]
	s_cbranch_execz .LBB0_839
	s_mov_b64 s[4:5], exec
	global_store_dword v149, v1, s[30:31] sc1

;     __device__ __forceinline__ bool run(const f32x4 (&v)[2][2][4][2], const Unit& u, int wr, int wc, int fr, int fq, PG8_LAS unsigned char* lds, int wid, int lane) const {
;     ...
;             __builtin_amdgcn_fence(__ATOMIC_ACQUIRE, "agent");
;             if (lane == 0) flag[0] = dead ? 1u : 0u;
;         }
;         asm volatile("s_waitcnt vmcnt(0) lgkmcnt(0)" ::: "memory"); __builtin_amdgcn_s_barrier(); asm volatile("" ::: "memory");
.LBB0_841:
	s_waitcnt vmcnt(0)
	s_and_b64 exec, exec, s[2:3]
	v_cndmask_b32_e64 v132, 0, 1, s[16:17]
	ds_write_b32 v149, v132 offset:10240
